# GEMM tile setup: redundant first accumulator zeroing (128 v_mov per wave per tile, only needed on the never-taken K<64 path) moved off the hot path
# speedup vs baseline: 1.0056x; 1.0056x over previous
; DI void gemm_phase(LAS unsigned char* lds, const Gemm g, const StaticOrder& S, const bool eperm) {
;     ...
;         for (int a = 0; a < 2; ++a)
; #pragma unroll
;             for (int b = 0; b < 2; ++b)
; #pragma unroll
;                 for (int m = 0; m < 4; ++m)
; #pragma unroll
;                     for (int n = 0; n < 2; ++n) acc[a][b][m][n] = (f32x4){0.f, 0.f, 0.f, 0.f};
.Lg_zero794:
	v_mov_b32_e32 v125, 0
	v_mov_b32_e32 v124, v125
	v_mov_b32_e32 v123, v125
	v_mov_b32_e32 v122, v125
	v_mov_b32_e32 v129, v125
	v_mov_b32_e32 v128, v125
	v_mov_b32_e32 v127, v125
	v_mov_b32_e32 v126, v125
	v_mov_b32_e32 v113, v125
	v_mov_b32_e32 v112, v125
	v_mov_b32_e32 v111, v125
	v_mov_b32_e32 v110, v125
	v_mov_b32_e32 v109, v125
	v_mov_b32_e32 v108, v125
	v_mov_b32_e32 v107, v125
	v_mov_b32_e32 v106, v125
	v_mov_b32_e32 v97, v125
	v_mov_b32_e32 v96, v125
	v_mov_b32_e32 v95, v125
	v_mov_b32_e32 v94, v125
	v_mov_b32_e32 v93, v125
	v_mov_b32_e32 v92, v125
	v_mov_b32_e32 v91, v125
	v_mov_b32_e32 v90, v125
	v_mov_b32_e32 v81, v125
	v_mov_b32_e32 v80, v125
	v_mov_b32_e32 v79, v125
	v_mov_b32_e32 v78, v125
	v_mov_b32_e32 v77, v125
	v_mov_b32_e32 v76, v125
	v_mov_b32_e32 v75, v125
	v_mov_b32_e32 v74, v125
	v_mov_b32_e32 v121, v125
	v_mov_b32_e32 v120, v125
	v_mov_b32_e32 v119, v125
	v_mov_b32_e32 v118, v125
	v_mov_b32_e32 v117, v125
	v_mov_b32_e32 v116, v125
	v_mov_b32_e32 v115, v125
	v_mov_b32_e32 v114, v125
	v_mov_b32_e32 v105, v125
	v_mov_b32_e32 v104, v125
	v_mov_b32_e32 v103, v125
	v_mov_b32_e32 v102, v125
	v_mov_b32_e32 v101, v125
	v_mov_b32_e32 v100, v125
	v_mov_b32_e32 v99, v125
	v_mov_b32_e32 v98, v125
	v_mov_b32_e32 v89, v125
	v_mov_b32_e32 v88, v125
	v_mov_b32_e32 v87, v125
	v_mov_b32_e32 v86, v125
	v_mov_b32_e32 v85, v125
	v_mov_b32_e32 v84, v125
	v_mov_b32_e32 v83, v125
	v_mov_b32_e32 v82, v125
	v_mov_b32_e32 v73, v125
	v_mov_b32_e32 v72, v125
	v_mov_b32_e32 v71, v125
	v_mov_b32_e32 v70, v125
	v_mov_b32_e32 v69, v125
	v_mov_b32_e32 v68, v125
	v_mov_b32_e32 v67, v125
	v_mov_b32_e32 v66, v125
	v_mov_b32_e32 v65, v125
	v_mov_b32_e32 v64, v125
	v_mov_b32_e32 v63, v125
	v_mov_b32_e32 v62, v125
	v_mov_b32_e32 v61, v125
	v_mov_b32_e32 v60, v125
	v_mov_b32_e32 v59, v125
	v_mov_b32_e32 v58, v125
	v_mov_b32_e32 v49, v125
	v_mov_b32_e32 v48, v125
	v_mov_b32_e32 v47, v125
	v_mov_b32_e32 v46, v125
	v_mov_b32_e32 v45, v125
	v_mov_b32_e32 v44, v125
	v_mov_b32_e32 v43, v125
	v_mov_b32_e32 v42, v125
	v_mov_b32_e32 v33, v125
	v_mov_b32_e32 v32, v125
	v_mov_b32_e32 v31, v125
	v_mov_b32_e32 v30, v125
	v_mov_b32_e32 v29, v125
	v_mov_b32_e32 v28, v125
	v_mov_b32_e32 v27, v125
	v_mov_b32_e32 v26, v125
	v_mov_b32_e32 v17, v125
	v_mov_b32_e32 v16, v125
	v_mov_b32_e32 v15, v125
	v_mov_b32_e32 v14, v125
	v_mov_b32_e32 v13, v125
	v_mov_b32_e32 v12, v125
	v_mov_b32_e32 v11, v125
	v_mov_b32_e32 v10, v125
	v_mov_b32_e32 v57, v125
	v_mov_b32_e32 v56, v125
	v_mov_b32_e32 v55, v125
	v_mov_b32_e32 v54, v125
	v_mov_b32_e32 v53, v125
	v_mov_b32_e32 v52, v125
	v_mov_b32_e32 v51, v125
	v_mov_b32_e32 v50, v125
	v_mov_b32_e32 v41, v125
	v_mov_b32_e32 v40, v125
	v_mov_b32_e32 v39, v125
	v_mov_b32_e32 v38, v125
	v_mov_b32_e32 v37, v125
	v_mov_b32_e32 v36, v125
	v_mov_b32_e32 v35, v125
	v_mov_b32_e32 v34, v125
	v_mov_b32_e32 v25, v125
	v_mov_b32_e32 v24, v125
	v_mov_b32_e32 v23, v125
	v_mov_b32_e32 v22, v125
	v_mov_b32_e32 v21, v125
	v_mov_b32_e32 v20, v125
	v_mov_b32_e32 v19, v125
	v_mov_b32_e32 v18, v125
	v_mov_b32_e32 v9, v125
	v_mov_b32_e32 v8, v125
	v_mov_b32_e32 v7, v125
	v_mov_b32_e32 v6, v125
	v_mov_b32_e32 v5, v125
	v_mov_b32_e32 v4, v125
	v_mov_b32_e32 v3, v125
	v_mov_b32_e32 v2, v125
	s_branch .LBB0_794

; DI void gemm_phase(LAS unsigned char* lds, const Gemm g, const StaticOrder& S, const bool eperm) {
;     ...
;         for (int t = 0; t < nt; t += 2) {
;             const bool last = (t == nt - 2);
;             const char* a1 = cA + (size_t)(t + 1) * kstep;
;             const char* a2 = last ? nA : cA + (size_t)(t + 2) * kstep; const char* b2 = last ? nB : cB + (size_t)(t + 2) * kstep;
;             const char* a3 = a2 + kstep; const char* b3 = b2 + kstep;
;     ...
;         for (int a = 0; a < 2; ++a)
; #pragma unroll
;             for (int b = 0; b < 2; ++b)
; #pragma unroll
;                 for (int m = 0; m < 4; ++m)
; #pragma unroll
;                     for (int n = 0; n < 2; ++n) acc[a][b][m][n] = (f32x4){0.f, 0.f, 0.f, 0.f};
.LBB0_791:
	s_andn2_b64 vcc, exec, s[20:21]
	s_cbranch_vccnz .Lg_zero794
	s_add_u32 s30, s30, 0x100
	s_addc_u32 s31, s31, 0
	s_add_u32 s0, s34, 0x80
	v_mov_b32_e32 v2, 0
	s_addc_u32 s1, s35, 0
	s_mov_b32 s6, 0
	v_mov_b32_e32 v3, v2
	v_mov_b32_e32 v4, v2
	v_mov_b32_e32 v5, v2
	v_mov_b32_e32 v6, v2
	v_mov_b32_e32 v7, v2
	v_mov_b32_e32 v8, v2
	v_mov_b32_e32 v9, v2
	v_mov_b32_e32 v18, v2
	v_mov_b32_e32 v19, v2
	v_mov_b32_e32 v20, v2
	v_mov_b32_e32 v21, v2
	v_mov_b32_e32 v22, v2
	v_mov_b32_e32 v23, v2
	v_mov_b32_e32 v24, v2
	v_mov_b32_e32 v25, v2
	v_mov_b32_e32 v34, v2
	v_mov_b32_e32 v35, v2
	v_mov_b32_e32 v36, v2
	v_mov_b32_e32 v37, v2
	v_mov_b32_e32 v38, v2
	v_mov_b32_e32 v39, v2
	v_mov_b32_e32 v40, v2
	v_mov_b32_e32 v41, v2
	v_mov_b32_e32 v50, v2
	v_mov_b32_e32 v51, v2
	v_mov_b32_e32 v52, v2
	v_mov_b32_e32 v53, v2
	v_mov_b32_e32 v54, v2
	v_mov_b32_e32 v55, v2
	v_mov_b32_e32 v56, v2
	v_mov_b32_e32 v57, v2
	v_mov_b32_e32 v10, v2
	v_mov_b32_e32 v11, v2
	v_mov_b32_e32 v12, v2
	v_mov_b32_e32 v13, v2
	v_mov_b32_e32 v14, v2
	v_mov_b32_e32 v15, v2
	v_mov_b32_e32 v16, v2
	v_mov_b32_e32 v17, v2
	v_mov_b32_e32 v26, v2
	v_mov_b32_e32 v27, v2
	v_mov_b32_e32 v28, v2
	v_mov_b32_e32 v29, v2
	v_mov_b32_e32 v30, v2
	v_mov_b32_e32 v31, v2
	v_mov_b32_e32 v32, v2
	v_mov_b32_e32 v33, v2
	v_mov_b32_e32 v42, v2
	v_mov_b32_e32 v43, v2
	v_mov_b32_e32 v44, v2
	v_mov_b32_e32 v45, v2
	v_mov_b32_e32 v46, v2
	v_mov_b32_e32 v47, v2
	v_mov_b32_e32 v48, v2
	v_mov_b32_e32 v49, v2
	v_mov_b32_e32 v58, v2
	v_mov_b32_e32 v59, v2
	v_mov_b32_e32 v60, v2
	v_mov_b32_e32 v61, v2
	v_mov_b32_e32 v62, v2
	v_mov_b32_e32 v63, v2
	v_mov_b32_e32 v64, v2
	v_mov_b32_e32 v65, v2
	v_mov_b32_e32 v66, v2
	v_mov_b32_e32 v67, v2
	v_mov_b32_e32 v68, v2
	v_mov_b32_e32 v69, v2
	v_mov_b32_e32 v70, v2
	v_mov_b32_e32 v71, v2
	v_mov_b32_e32 v72, v2
	v_mov_b32_e32 v73, v2
	v_mov_b32_e32 v82, v2
	v_mov_b32_e32 v83, v2
	v_mov_b32_e32 v84, v2
	v_mov_b32_e32 v85, v2
	v_mov_b32_e32 v86, v2
	v_mov_b32_e32 v87, v2
	v_mov_b32_e32 v88, v2
	v_mov_b32_e32 v89, v2
	v_mov_b32_e32 v98, v2
	v_mov_b32_e32 v99, v2
	v_mov_b32_e32 v100, v2
	v_mov_b32_e32 v101, v2
	v_mov_b32_e32 v102, v2
	v_mov_b32_e32 v103, v2
	v_mov_b32_e32 v104, v2
	v_mov_b32_e32 v105, v2
	v_mov_b32_e32 v114, v2
	v_mov_b32_e32 v115, v2
	v_mov_b32_e32 v116, v2
	v_mov_b32_e32 v117, v2
	v_mov_b32_e32 v118, v2
	v_mov_b32_e32 v119, v2
	v_mov_b32_e32 v120, v2
	v_mov_b32_e32 v121, v2
	v_mov_b32_e32 v74, v2
	v_mov_b32_e32 v75, v2
	v_mov_b32_e32 v76, v2
	v_mov_b32_e32 v77, v2
	v_mov_b32_e32 v78, v2
	v_mov_b32_e32 v79, v2
	v_mov_b32_e32 v80, v2
	v_mov_b32_e32 v81, v2
	v_mov_b32_e32 v90, v2
	v_mov_b32_e32 v91, v2
	v_mov_b32_e32 v92, v2
	v_mov_b32_e32 v93, v2
	v_mov_b32_e32 v94, v2
	v_mov_b32_e32 v95, v2
	v_mov_b32_e32 v96, v2
	v_mov_b32_e32 v97, v2
	v_mov_b32_e32 v106, v2
	v_mov_b32_e32 v107, v2
	v_mov_b32_e32 v108, v2
	v_mov_b32_e32 v109, v2
	v_mov_b32_e32 v110, v2
	v_mov_b32_e32 v111, v2
	v_mov_b32_e32 v112, v2
	v_mov_b32_e32 v113, v2
	v_mov_b32_e32 v126, v2
	v_mov_b32_e32 v127, v2
	v_mov_b32_e32 v128, v2
	v_mov_b32_e32 v129, v2
	v_mov_b32_e32 v122, v2
	v_mov_b32_e32 v123, v2
	v_mov_b32_e32 v124, v2
	v_mov_b32_e32 v125, v2
